# fast path v13: v12 (barrier before last four tile-B PV MFMAs) with row-sum adds moved to the serial cvt stretch / tile-A PV gaps so pre-barrier gaps carry only staging writes
# baseline (speedup 1.0000x reference)
; #define MFMA32(a, b, c) __builtin_amdgcn_mfma_f32_32x32x16_bf16((a), (b), (c), 0, 0, 0)
; DI unsigned pk_bf16(float lo, float hi) { f32x2 v = {lo, hi}; bf16v2 b = __builtin_convertvector(v, bf16v2); return __builtin_bit_cast(unsigned, b); }
; DI int crow(int r, int h) { return (r & 3) + 8 * (r >> 2) + 4 * h; }
; DI void attn_item(const Params& p, int g, int seq, int hd, int qt, int m, char* smem, int split_j, int sub) {
;     ...
;     bf16x8 kf[4], vf[2][4];
; #pragma unroll
;     for (int s = 0; s < 4; ++s) kf[s] = *(const bf16x8*)(Kb + l31 * 72 + s * 16 + h * 8);
; #pragma unroll
;     for (int s2 = 0; s2 < 2; ++s2)
; #pragma unroll
;       for (int dt = 0; dt < 4; ++dt) vf[s2][dt] = *(const bf16x8*)(Vb + (dt * 32 + l31) * 40 + s2 * 16 + h * 8);
;     __builtin_amdgcn_sched_barrier(0);
;     f32x16 X;
; #pragma unroll
;     for (int r = 0; r < 16; ++r) X[r] = 0.f;
; #pragma unroll
;     for (int s = 0; s < 4; ++s) X = MFMA32(kf[s], qf[s], X);
;     if (farL || farR) {
; #pragma unroll
;       for (int r = 0; r < 16; ++r) X[r] = __builtin_amdgcn_exp2f(X[r]);
;     } else {
;       const int rel0 = k0 - (qw0 + l31) + 128;
; #pragma unroll
;       for (int r = 0; r < 16; ++r) { int idx = rel0 + crow(r, h); idx = idx < 0 ? 0 : (idx > 256 ? 256 : idx); X[r] = __builtin_amdgcn_exp2f(X[r] + tab[idx]); }
;     }
;     bf16x8 pf[2];
; #pragma unroll
;     for (int s2 = 0; s2 < 2; ++s2) {
;       u32x4 w; w.x = pk_bf16(X[8 * s2], X[8 * s2 + 1]); w.y = pk_bf16(X[8 * s2 + 2], X[8 * s2 + 3]); w.z = pk_bf16(X[8 * s2 + 4], X[8 * s2 + 5]); w.w = pk_bf16(X[8 * s2 + 6], X[8 * s2 + 7]);
;       ls2 += (f32x2){X[8 * s2], X[8 * s2 + 1]}; ls2 += (f32x2){X[8 * s2 + 2], X[8 * s2 + 3]};
;       ls2 += (f32x2){X[8 * s2 + 4], X[8 * s2 + 5]}; ls2 += (f32x2){X[8 * s2 + 6], X[8 * s2 + 7]};
;       pf[s2] = __builtin_bit_cast(bf16x8, w);
;     }
; #pragma unroll
;     for (int s2 = 0; s2 < 2; ++s2)
; #pragma unroll
;       for (int dt = 0; dt < 4; ++dt) O[dt] = MFMA32(pf[s2], vf[s2][dt], O[dt]);
.Lat2_qka:
	s_waitcnt lgkmcnt(3)
	v_mfma_f32_32x32x16_bf16 v[64:79], v[64:67], v[104:107], 0
	ds_read_b128 v[220:223], v192 offset:4608
	ds_read_b128 v[224:227], v192 offset:4640
	ds_read_b128 v[236:239], v192 offset:4672
	ds_read_b128 v[240:243], v192 offset:4704
	s_waitcnt lgkmcnt(6)
	v_mfma_f32_32x32x16_bf16 v[64:79], v[80:83], v[108:111], v[64:79]
	ds_read_b128 v[156:159], v244 offset:18432
	ds_read_b128 v[160:163], v244 offset:20992
	s_waitcnt lgkmcnt(7)
	v_mfma_f32_32x32x16_bf16 v[64:79], v[84:87], v[112:115], v[64:79]
	ds_read_b128 v[164:167], v244 offset:23552
	ds_read_b128 v[152:155], v244 offset:26112
	s_waitcnt lgkmcnt(8)
	v_mfma_f32_32x32x16_bf16 v[64:79], v[88:91], v[116:119], v[64:79]
	ds_read_b128 v[148:151], v244 offset:18464
	ds_read_b128 v[144:147], v244 offset:21024
	ds_read_b128 v[136:139], v244 offset:23584
	ds_read_b128 v[140:143], v244 offset:26144
	s_waitcnt lgkmcnt(11)
	v_mfma_f32_32x32x16_bf16 v[80:95], v[220:223], v[104:107], 0
	s_waitcnt lgkmcnt(10)
	v_mfma_f32_32x32x16_bf16 v[80:95], v[224:227], v[108:111], v[80:95]
	v_exp_f32_e32 v64, v64
	v_exp_f32_e32 v65, v65
	v_exp_f32_e32 v66, v66
	v_exp_f32_e32 v67, v67
	v_exp_f32_e32 v68, v68
	v_exp_f32_e32 v69, v69
	s_waitcnt lgkmcnt(9)
	v_mfma_f32_32x32x16_bf16 v[80:95], v[236:239], v[112:115], v[80:95]
	v_exp_f32_e32 v70, v70
	v_exp_f32_e32 v71, v71
	v_exp_f32_e32 v72, v72
	v_exp_f32_e32 v73, v73
	v_exp_f32_e32 v74, v74
	v_exp_f32_e32 v75, v75
	s_waitcnt lgkmcnt(8)
	v_mfma_f32_32x32x16_bf16 v[80:95], v[240:243], v[116:119], v[80:95]
	v_exp_f32_e32 v76, v76
	v_exp_f32_e32 v77, v77
	v_exp_f32_e32 v78, v78
	v_exp_f32_e32 v79, v79
	v_cvt_pk_bf16_f32 v220, v64, v65
	v_cvt_pk_bf16_f32 v221, v66, v67
	v_cvt_pk_bf16_f32 v222, v68, v69
	v_cvt_pk_bf16_f32 v223, v70, v71
	v_cvt_pk_bf16_f32 v224, v72, v73
	v_cvt_pk_bf16_f32 v225, v74, v75
	v_cvt_pk_bf16_f32 v226, v76, v77
	v_cvt_pk_bf16_f32 v227, v78, v79
	v_add_f32_e32 v246, v66, v70
	v_add_f32_e32 v247, v67, v71
	v_add_f32_e32 v186, v186, v64
	v_add_f32_e32 v187, v187, v65
	v_add_f32_e32 v246, v246, v74
	v_add_f32_e32 v247, v247, v75
	v_add_f32_e32 v186, v186, v68
	v_add_f32_e32 v187, v187, v69
	v_add_f32_e32 v246, v246, v78
	v_add_f32_e32 v247, v247, v79
	v_add_f32_e32 v186, v186, v72
	v_add_f32_e32 v187, v187, v73
	v_add_f32_e32 v186, v186, v76
	v_add_f32_e32 v187, v187, v77
	v_add_f32_e32 v186, v186, v246
	v_add_f32_e32 v187, v187, v247
	s_waitcnt lgkmcnt(7)
	v_mfma_f32_32x32x16_bf16 v[48:63], v[220:223], v[156:159], v[48:63]
	ds_read_b128 v[156:159], v244 offset:28672
	v_exp_f32_e32 v80, v80
	v_exp_f32_e32 v81, v81
	v_exp_f32_e32 v82, v82
	s_waitcnt lgkmcnt(7)
	v_mfma_f32_32x32x16_bf16 v[32:47], v[220:223], v[160:163], v[32:47]
	ds_read_b128 v[160:163], v244 offset:31232
	v_exp_f32_e32 v83, v83
	v_exp_f32_e32 v84, v84
	v_exp_f32_e32 v85, v85
	s_waitcnt lgkmcnt(7)
	v_mfma_f32_32x32x16_bf16 v[16:31], v[220:223], v[164:167], v[16:31]
	ds_read_b128 v[164:167], v244 offset:33792
	v_exp_f32_e32 v86, v86
	v_exp_f32_e32 v87, v87
	v_exp_f32_e32 v88, v88
	s_waitcnt lgkmcnt(7)
	v_mfma_f32_32x32x16_bf16 v[0:15], v[220:223], v[152:155], v[0:15]
	ds_read_b128 v[152:155], v244 offset:36352
	v_exp_f32_e32 v89, v89
	v_exp_f32_e32 v90, v90
	v_exp_f32_e32 v91, v91
	s_waitcnt lgkmcnt(7)
	v_mfma_f32_32x32x16_bf16 v[48:63], v[224:227], v[148:151], v[48:63]
	ds_read_b128 v[148:151], v244 offset:28704
	v_exp_f32_e32 v92, v92
	v_exp_f32_e32 v93, v93
	v_exp_f32_e32 v94, v94
	v_exp_f32_e32 v95, v95
	s_waitcnt lgkmcnt(7)
	v_mfma_f32_32x32x16_bf16 v[32:47], v[224:227], v[144:147], v[32:47]
	ds_read_b128 v[144:147], v244 offset:31264
	v_cvt_pk_bf16_f32 v236, v80, v81
	v_cvt_pk_bf16_f32 v237, v82, v83
	v_cvt_pk_bf16_f32 v238, v84, v85
	v_add_f32_e32 v246, v82, v86
	v_add_f32_e32 v247, v83, v87
	v_add_f32_e32 v186, v186, v80
	v_add_f32_e32 v187, v187, v81
	v_add_f32_e32 v246, v246, v90
	v_add_f32_e32 v247, v247, v91
	s_waitcnt lgkmcnt(7)
	v_mfma_f32_32x32x16_bf16 v[16:31], v[224:227], v[136:139], v[16:31]
	ds_read_b128 v[136:139], v244 offset:33824
	v_cvt_pk_bf16_f32 v239, v86, v87
	v_cvt_pk_bf16_f32 v240, v88, v89
	v_cvt_pk_bf16_f32 v241, v90, v91
	v_add_f32_e32 v186, v186, v84
	v_add_f32_e32 v187, v187, v85
	v_add_f32_e32 v246, v246, v94
	v_add_f32_e32 v247, v247, v95
	v_add_f32_e32 v186, v186, v88
	s_waitcnt lgkmcnt(7)
	v_mfma_f32_32x32x16_bf16 v[0:15], v[224:227], v[140:143], v[0:15]
	ds_read_b128 v[140:143], v244 offset:36384
	v_cvt_pk_bf16_f32 v242, v92, v93
	v_cvt_pk_bf16_f32 v243, v94, v95
	v_add_f32_e32 v187, v187, v89
	v_add_f32_e32 v186, v186, v92
	v_add_f32_e32 v187, v187, v93
	v_add_f32_e32 v186, v186, v246
	v_add_f32_e32 v187, v187, v247
	s_andn2_b64 vcc, exec, s[8:9]
	s_cbranch_vccnz .Lat2_pvplain
	s_add_i32 s10, s15, 1
	s_cmp_lt_u32 s10, s73
	s_cbranch_scc0 .Lat2_pvw
; #define MFMA32(a, b, c) __builtin_amdgcn_mfma_f32_32x32x16_bf16((a), (b), (c), 0, 0, 0)
; DI unsigned pk_bf16(float lo, float hi) { f32x2 v = {lo, hi}; bf16v2 b = __builtin_convertvector(v, bf16v2); return __builtin_bit_cast(unsigned, b); }
; DI void attn_item(const Params& p, int g, int seq, int hd, int qt, int m, char* smem, int split_j, int sub) {
;     ...
;     bf16x8 pf[2];
; #pragma unroll
;     for (int s2 = 0; s2 < 2; ++s2) {
;       u32x4 w; w.x = pk_bf16(X[8 * s2], X[8 * s2 + 1]); w.y = pk_bf16(X[8 * s2 + 2], X[8 * s2 + 3]); w.z = pk_bf16(X[8 * s2 + 4], X[8 * s2 + 5]); w.w = pk_bf16(X[8 * s2 + 6], X[8 * s2 + 7]);
;       ls2 += (f32x2){X[8 * s2], X[8 * s2 + 1]}; ls2 += (f32x2){X[8 * s2 + 2], X[8 * s2 + 3]};
;       ls2 += (f32x2){X[8 * s2 + 4], X[8 * s2 + 5]}; ls2 += (f32x2){X[8 * s2 + 6], X[8 * s2 + 7]};
;       pf[s2] = __builtin_bit_cast(bf16x8, w);
;     }
; #pragma unroll
;     for (int s2 = 0; s2 < 2; ++s2)
; #pragma unroll
;       for (int dt = 0; dt < 4; ++dt) O[dt] = MFMA32(pf[s2], vf[s2][dt], O[dt]);
;   };
;   load_tile(0, rkA, rvA0, rvA1);
;   load_tile(1, rkB, rvB0, rvB1);
;   __syncthreads();
;   store_tile(0, rkA, rvA0, rvA1);
;   store_tile(1, rkB, rvB0, rvB1);
;   __syncthreads();
;   for (int it = 0; it < npairs; ++it) {
;     const int set = it & 1;
;     if (it + 1 < npairs) { load_tile(2 * it + 2, rkA, rvA0, rvA1); load_tile(2 * it + 3, rkB, rvB0, rvB1); }
;     compute(2 * it, 2 * set);
;     compute(2 * it + 1, 2 * set + 1);
;     if (it + 1 < npairs) { store_tile(2 * (set ^ 1), rkA, rvA0, rvA1); store_tile(2 * (set ^ 1) + 1, rkB, rvB0, rvB1); }
;     __syncthreads();
	s_xor_b32 s7, s16, 2
	s_mul_i32 s8, s7, 0x2800
	s_add_i32 s8, s8, 32
	s_mulk_i32 s7, 0x1200
	v_add_u32_e32 v192, s7, v169
	v_add3_u32 v244, s8, v189, v190
	s_addk_i32 s8, 0x2800
	s_add_i32 s13, s13, 64
	s_add_i32 s6, s6, 2
	s_mov_b32 s15, s10
	s_mov_b64 s[20:21], 0x1000
	s_waitcnt lgkmcnt(7)
	v_mfma_f32_32x32x16_bf16 v[48:63], v[236:239], v[156:159], v[48:63]
	s_waitcnt vmcnt(5)
	ds_write_b128 v192, v[96:99]
	s_waitcnt vmcnt(4)
	ds_write_b128 v244, v[100:103] offset:18432
	s_waitcnt lgkmcnt(8)
	v_mfma_f32_32x32x16_bf16 v[32:47], v[236:239], v[160:163], v[32:47]
	s_waitcnt vmcnt(3)
	ds_write_b128 v244, v[120:123] offset:23552
	s_waitcnt vmcnt(2)
	ds_write_b128 v192, v[124:127] offset:4608
	s_waitcnt lgkmcnt(9)
	v_mfma_f32_32x32x16_bf16 v[16:31], v[236:239], v[164:167], v[16:31]
	v_add3_u32 v192, s8, v189, v190
	s_waitcnt vmcnt(1)
	ds_write_b128 v192, v[128:131] offset:18432
	s_waitcnt lgkmcnt(9)
	v_mfma_f32_32x32x16_bf16 v[0:15], v[236:239], v[152:155], v[0:15]
	s_waitcnt vmcnt(0)
	ds_write_b128 v192, v[132:135] offset:23552
	s_add_i32 s10, s6, -3
	s_and_b32 s16, s10, 2
	s_mul_i32 s10, s16, 0x1200
	s_mul_i32 s18, s16, 0x2800
	v_add_u32_e32 v192, s10, v191
	v_add_u32_e32 v244, s18, v196
	s_waitcnt lgkmcnt(0)
	s_barrier
	v_mfma_f32_32x32x16_bf16 v[48:63], v[240:243], v[148:151], v[48:63]
	ds_read_b128 v[64:67], v192
	ds_read_b128 v[80:83], v192 offset:32
	ds_read_b128 v[84:87], v192 offset:64
	ds_read_b128 v[88:91], v192 offset:96
	s_add_i32 s50, s6, -1
	s_lshl_b64 s[10:11], s[50:51], 12
	v_lshl_add_u64 v[220:221], v[172:173], 0, s[10:11]
	v_mfma_f32_32x32x16_bf16 v[32:47], v[240:243], v[144:147], v[32:47]
	global_load_dwordx4 v[96:99], v[220:221], off
	s_lshl_b64 s[10:11], s[50:51], 13
	v_lshl_add_u64 v[222:223], v[170:171], 0, s[10:11]
	global_load_dwordx4 v[100:103], v[222:223], off
	v_lshl_add_u64 v[224:225], v[222:223], 0, s[20:21]
	v_mfma_f32_32x32x16_bf16 v[16:31], v[240:243], v[136:139], v[16:31]
	global_load_dwordx4 v[120:123], v[224:225], off
	s_mov_b32 s7, s51
	s_lshl_b64 s[10:11], s[6:7], 12
	v_lshl_add_u64 v[220:221], v[172:173], 0, s[10:11]
	global_load_dwordx4 v[124:127], v[220:221], off
	s_lshl_b64 s[10:11], s[6:7], 13
	v_lshl_add_u64 v[222:223], v[170:171], 0, s[10:11]
	v_mfma_f32_32x32x16_bf16 v[0:15], v[240:243], v[140:143], v[0:15]
	global_load_dwordx4 v[128:131], v[222:223], off
	v_lshl_add_u64 v[224:225], v[222:223], 0, s[20:21]
	global_load_dwordx4 v[132:135], v[224:225], off
	s_add_i32 s7, s14, s13
	s_cmpk_lt_i32 s7, 0xff42
	s_cselect_b32 s19, 1, 0
	s_cmpk_gt_i32 s7, 0x9e
	s_cselect_b32 s50, 1, 0
	s_cmp_eq_u32 s17, 2
	s_cselect_b32 s50, s50, 0
	s_or_b32 s19, s19, s50
	s_mov_b64 s[8:9], -1
	s_cmp_lg_u32 s19, 0
	s_cbranch_scc1 .Lat2_qka
	s_waitcnt lgkmcnt(0)
	s_branch .LBB0_319
.Lat2_pvw:
	s_xor_b32 s7, s16, 2
	s_mul_i32 s8, s7, 0x2800
	s_add_i32 s8, s8, 32
	s_mulk_i32 s7, 0x1200
	v_add_u32_e32 v192, s7, v169
	v_add3_u32 v244, s8, v189, v190
	s_addk_i32 s8, 0x2800
	s_waitcnt lgkmcnt(7)
	v_mfma_f32_32x32x16_bf16 v[48:63], v[236:239], v[156:159], v[48:63]
	s_waitcnt vmcnt(5)
	ds_write_b128 v192, v[96:99]
	s_waitcnt lgkmcnt(7)
	v_mfma_f32_32x32x16_bf16 v[32:47], v[236:239], v[160:163], v[32:47]
	s_waitcnt vmcnt(4)
	ds_write_b128 v244, v[100:103] offset:18432
	s_waitcnt lgkmcnt(7)
	v_mfma_f32_32x32x16_bf16 v[16:31], v[236:239], v[164:167], v[16:31]
	s_waitcnt vmcnt(3)
	ds_write_b128 v244, v[120:123] offset:23552
	s_waitcnt lgkmcnt(7)
	v_mfma_f32_32x32x16_bf16 v[0:15], v[236:239], v[152:155], v[0:15]
	s_waitcnt vmcnt(2)
	ds_write_b128 v192, v[124:127] offset:4608
	s_waitcnt lgkmcnt(7)
	v_mfma_f32_32x32x16_bf16 v[48:63], v[240:243], v[148:151], v[48:63]
	v_add3_u32 v192, s8, v189, v190
	s_waitcnt vmcnt(1)
	ds_write_b128 v192, v[128:131] offset:18432
	s_waitcnt lgkmcnt(7)
	v_mfma_f32_32x32x16_bf16 v[32:47], v[240:243], v[144:147], v[32:47]
	s_waitcnt vmcnt(0)
	ds_write_b128 v192, v[132:135] offset:23552
	s_waitcnt lgkmcnt(7)
	v_mfma_f32_32x32x16_bf16 v[16:31], v[240:243], v[136:139], v[16:31]
	s_waitcnt lgkmcnt(6)
	v_mfma_f32_32x32x16_bf16 v[0:15], v[240:243], v[140:143], v[0:15]
	s_branch .Lat2_bot
.Lat2_pvplain:
	s_waitcnt lgkmcnt(7)
	v_mfma_f32_32x32x16_bf16 v[48:63], v[236:239], v[156:159], v[48:63]
	s_waitcnt lgkmcnt(6)
	v_mfma_f32_32x32x16_bf16 v[32:47], v[236:239], v[160:163], v[32:47]
	s_waitcnt lgkmcnt(5)
	v_mfma_f32_32x32x16_bf16 v[16:31], v[236:239], v[164:167], v[16:31]
	s_waitcnt lgkmcnt(4)
	v_mfma_f32_32x32x16_bf16 v[0:15], v[236:239], v[152:155], v[0:15]
	s_waitcnt lgkmcnt(3)
	v_mfma_f32_32x32x16_bf16 v[48:63], v[240:243], v[148:151], v[48:63]
	s_waitcnt lgkmcnt(2)
	v_mfma_f32_32x32x16_bf16 v[32:47], v[240:243], v[144:147], v[32:47]
	s_waitcnt lgkmcnt(1)
	v_mfma_f32_32x32x16_bf16 v[16:31], v[240:243], v[136:139], v[16:31]
	s_waitcnt lgkmcnt(0)
	v_mfma_f32_32x32x16_bf16 v[0:15], v[240:243], v[140:143], v[0:15]
